# NSA tile: first V-fragment reads issued before the max/test chain (LDS latency under VALU)
# baseline (speedup 1.0000x reference)
; #define LAS __attribute__((address_space(3)))
; DI float fexp2(float x) { return __builtin_amdgcn_exp2f(x); }
; DI f32x16 mfma32(bf16x8 a, bf16x8 b, f32x16 c) { return __builtin_amdgcn_mfma_f32_32x32x16_bf16(a, b, c, 0, 0, 0); }
; DI void pv_sub(const LAS unsigned char* vt, int vstride, int koff_bytes, const f32x16& p, f32x16 (&o)[2], int r, int hh) {
;     const bf16x8 pf0 = pack8<0>(p), pf1 = pack8<1>(p);
; #pragma unroll
;     for (int st = 0; st < 2; ++st) {
;         u32x2 lo[2], hi[2];
; #pragma unroll
;         for (int u = 0; u < 2; ++u) {
;             const LAS unsigned char* a = vt + (32 * u + r) * vstride + koff_bytes + 32 * st + 8 * hh;
;             lo[u] = *(const LAS u32x2*)a; hi[u] = *(const LAS u32x2*)(a + 16);
;         }
;         __builtin_amdgcn_sched_barrier(0);
; #pragma unroll
;         for (int u = 0; u < 2; ++u) { u32x4 v; v.x = lo[u].x; v.y = lo[u].y; v.z = hi[u].x; v.w = hi[u].y; o[u] = mfma32(__builtin_bit_cast(bf16x8, v), st ? pf1 : pf0, o[u]); }
;     }
; }
; DI void softmax_lazy(f32x16 (&s)[2], float& m, float& l, f32x16 (&o)[2], int hh) {
;     ...
;     float sum = 0.f;
; #pragma unroll
;     for (int t = 0; t < 2; ++t)
; #pragma unroll
;         for (int i = 0; i < 16; ++i) { s[t][i] = fexp2(s[t][i]); sum += s[t][i]; }
;     sum += __shfl_xor(sum, 32);
;     l += sum;
.LBB0_2419:
	v_add3_u32 v0, s0, v211, v242
	v_add_u32_e32 v2, 0xa800, v0
	v_add_u32_e32 v0, 0xb800, v0
	v_exp_f32_e32 v160, v160
	v_exp_f32_e32 v161, v161
	v_exp_f32_e32 v162, v162
	v_exp_f32_e32 v163, v163
	v_exp_f32_e32 v164, v164
	v_exp_f32_e32 v165, v165
	v_exp_f32_e32 v166, v166
	v_exp_f32_e32 v167, v167
	v_add_f32_e32 v3, v161, v160
	v_add_f32_e32 v3, v162, v3
	v_add_f32_e32 v3, v163, v3
	v_add_f32_e32 v3, v164, v3
	v_add_f32_e32 v3, v165, v3
	v_add_f32_e32 v3, v166, v3
	v_add_f32_e32 v3, v167, v3
	v_cvt_pk_bf16_f32 v8, v160, v161
	v_cvt_pk_bf16_f32 v9, v162, v163
	v_cvt_pk_bf16_f32 v10, v164, v165
	v_cvt_pk_bf16_f32 v11, v166, v167
	v_exp_f32_e32 v168, v168
	v_exp_f32_e32 v169, v169
	v_exp_f32_e32 v170, v170
	v_exp_f32_e32 v171, v171
	s_waitcnt lgkmcnt(0)
	v_mfma_f32_32x32x16_bf16 v[128:143], v[56:59], v[8:11], v[128:143]
	v_exp_f32_e32 v172, v172
	v_exp_f32_e32 v173, v173
	v_exp_f32_e32 v174, v174
	v_exp_f32_e32 v175, v175
	v_mfma_f32_32x32x16_bf16 v[112:127], v[60:63], v[8:11], v[112:127]
	ds_read2_b64 v[64:67], v2 offset0:196 offset1:198
	ds_read2_b64 v[68:71], v0 offset0:228 offset1:230
	v_add_f32_e32 v3, v168, v3
	v_add_f32_e32 v3, v169, v3
	v_add_f32_e32 v3, v170, v3
	v_add_f32_e32 v3, v171, v3
	v_add_f32_e32 v3, v172, v3
	v_add_f32_e32 v3, v173, v3
	v_add_f32_e32 v3, v174, v3
	v_add_f32_e32 v3, v175, v3
	v_cvt_pk_bf16_f32 v12, v168, v169
	v_cvt_pk_bf16_f32 v13, v170, v171
	v_cvt_pk_bf16_f32 v14, v172, v173
	v_cvt_pk_bf16_f32 v15, v174, v175
	v_exp_f32_e32 v144, v144
	v_exp_f32_e32 v145, v145
	v_exp_f32_e32 v146, v146
	v_exp_f32_e32 v147, v147
	s_waitcnt lgkmcnt(0)
	v_mfma_f32_32x32x16_bf16 v[128:143], v[64:67], v[12:15], v[128:143]
	v_exp_f32_e32 v148, v148
	v_exp_f32_e32 v149, v149
	v_exp_f32_e32 v150, v150
	v_exp_f32_e32 v151, v151
	v_mfma_f32_32x32x16_bf16 v[112:127], v[68:71], v[12:15], v[112:127]
	ds_read2_b64 v[72:75], v2 offset0:200 offset1:202
	ds_read2_b64 v[76:79], v0 offset0:232 offset1:234
	v_add_f32_e32 v3, v144, v3
	v_add_f32_e32 v3, v145, v3
	v_add_f32_e32 v3, v146, v3
	v_add_f32_e32 v3, v147, v3
	v_add_f32_e32 v3, v148, v3
	v_add_f32_e32 v3, v149, v3
	v_add_f32_e32 v3, v150, v3
	v_add_f32_e32 v3, v151, v3
	v_cvt_pk_bf16_f32 v16, v144, v145
	v_cvt_pk_bf16_f32 v17, v146, v147
	v_cvt_pk_bf16_f32 v18, v148, v149
	v_cvt_pk_bf16_f32 v19, v150, v151
	v_exp_f32_e32 v152, v152
	v_exp_f32_e32 v153, v153
	v_exp_f32_e32 v154, v154
	v_exp_f32_e32 v155, v155
	s_waitcnt lgkmcnt(0)
	v_mfma_f32_32x32x16_bf16 v[128:143], v[72:75], v[16:19], v[128:143]
	v_exp_f32_e32 v156, v156
	v_exp_f32_e32 v157, v157
	v_exp_f32_e32 v158, v158
	v_exp_f32_e32 v159, v159
	v_mfma_f32_32x32x16_bf16 v[112:127], v[76:79], v[16:19], v[112:127]
	ds_read2_b64 v[144:147], v2 offset0:204 offset1:206
	ds_read2_b64 v[148:151], v0 offset0:236 offset1:238
	v_add_f32_e32 v3, v152, v3
	v_add_f32_e32 v3, v153, v3
	v_add_f32_e32 v3, v154, v3
	v_add_f32_e32 v3, v155, v3
	v_add_f32_e32 v3, v156, v3
	v_add_f32_e32 v3, v157, v3
	v_add_f32_e32 v3, v158, v3
	v_add_f32_e32 v3, v159, v3
	v_mov_b32_e32 v7, v3
	v_cvt_pk_bf16_f32 v52, v152, v153
	v_cvt_pk_bf16_f32 v53, v154, v155
	v_cvt_pk_bf16_f32 v54, v156, v157
	v_cvt_pk_bf16_f32 v55, v158, v159
	v_permlane32_swap_b32_e32 v7, v3
	v_add_f32_e32 v3, v3, v7
	v_add_f32_e32 v245, v245, v3
	s_waitcnt lgkmcnt(0)
	v_mfma_f32_32x32x16_bf16 v[128:143], v[144:147], v[52:55], v[128:143]
	v_mfma_f32_32x32x16_bf16 v[112:127], v[148:151], v[52:55], v[112:127]

; #define LAS __attribute__((address_space(3)))
; DI float fexp2(float x) { return __builtin_amdgcn_exp2f(x); }
; DI f32x16 mfma32(bf16x8 a, bf16x8 b, f32x16 c) { return __builtin_amdgcn_mfma_f32_32x32x16_bf16(a, b, c, 0, 0, 0); }
; DI void pv_sub(const LAS unsigned char* vt, int vstride, int koff_bytes, const f32x16& p, f32x16 (&o)[2], int r, int hh) {
;     ...
;         u32x2 lo[2], hi[2];
; #pragma unroll
;         for (int u = 0; u < 2; ++u) {
;             const LAS unsigned char* a = vt + (32 * u + r) * vstride + koff_bytes + 32 * st + 8 * hh;
;             lo[u] = *(const LAS u32x2*)a; hi[u] = *(const LAS u32x2*)(a + 16);
;         }
; DI void softmax_lazy(f32x16 (&s)[2], float& m, float& l, f32x16 (&o)[2], int hh) {
;     float mx = s[0][0];
; #pragma unroll
;     for (int i = 1; i < 16; ++i) mx = fmaxf(mx, s[0][i]);
; #pragma unroll
;     for (int i = 0; i < 16; ++i) mx = fmaxf(mx, s[1][i]);
;     mx = fmaxf(mx, __shfl_xor(mx, 32));
;     const bool live = mx > -1e29f;
;     const bool slow = live && (mx > 32.f || (mx < -32.f && l == 0.f));
;     if (__ballot(slow) != 0ull) {
;         const float shift = (live && (mx > 0.f || l == 0.f)) ? mx : 0.f;
;         const float alpha = (l == 0.f) ? 0.f : fexp2(-shift);
;         const bf16x8 of = ones_frag(hh), sf = ref_frag(-shift, 0.f, hh);
;         s[0] = mfma32(of, sf, s[0]); s[1] = mfma32(of, sf, s[1]);
;         l *= alpha; m += shift;
;         o[0] *= alpha; o[1] *= alpha;
;     }
.LBB0_2430:
	s_or_b64 exec, exec, s[6:7]
	v_add3_u32 v13, s0, v211, v242
	v_add_u32_e32 v14, 0xa800, v13
	v_add_u32_e32 v13, 0xb800, v13
	ds_read2_b64 v[56:59], v14 offset0:192 offset1:194
	ds_read2_b64 v[60:63], v13 offset0:224 offset1:226
	v_max_f32_e32 v0, v161, v161
	v_max_f32_e32 v2, v160, v160
	v_max_f32_e32 v0, v2, v0
	v_max3_f32 v0, v0, v162, v163
	v_max3_f32 v0, v0, v164, v165
	v_max3_f32 v0, v0, v166, v167
	v_max3_f32 v0, v0, v168, v169
	v_max3_f32 v0, v0, v170, v171
	v_max3_f32 v0, v0, v172, v173
	v_max3_f32 v0, v0, v174, v175
	v_max3_f32 v0, v0, v144, v145
	v_max3_f32 v0, v0, v146, v147
	v_max3_f32 v0, v0, v148, v149
	v_max3_f32 v0, v0, v150, v151
	v_max3_f32 v0, v0, v152, v153
	v_max3_f32 v0, v0, v154, v155
	v_max3_f32 v0, v0, v156, v157
	v_max3_f32 v0, v0, v158, v159
	v_mov_b32_e32 v2, v0
	s_mov_b64 s[30:31], 0
	s_nop 0
	v_permlane32_swap_b32_e32 v2, v0
	v_max_f32_e32 v2, v2, v2
	v_max_f32_e32 v0, v0, v2
	v_cmp_lt_f32_e64 s[4:5], s40, v0
	v_cmp_lt_f32_e64 s[30:31], s63, v0
	v_cmp_gt_f32_e64 s[34:35], s76, v0
	v_cmp_eq_f32_e32 vcc, 0, v245
	s_and_b64 s[34:35], s[34:35], vcc
	s_or_b64 s[30:31], s[30:31], s[34:35]
	s_and_b64 s[30:31], s[30:31], s[4:5]
	s_cmp_eq_u64 s[30:31], 0
	s_cbranch_scc1 .LBB0_2419
	v_cmp_lt_f32_e32 vcc, 0, v0
	v_cmp_eq_f32_e64 s[6:7], 0, v245
	s_or_b64 s[30:31], vcc, s[6:7]
	s_and_b64 vcc, s[4:5], s[30:31]
	v_cndmask_b32_e32 v7, 0, v0, vcc
	v_exp_f32_e64 v0, -v7
	v_mov_b32_e32 v3, v1
	v_add_f32_e32 v4, v4, v7
	v_cndmask_b32_e64 v8, v0, 0, s[6:7]
	v_cvt_pk_bf16_f32 v0, -v7, s0
	v_perm_b32 v0, 0, v0, v229
	v_lshlrev_b32_e32 v2, 16, v0
	v_sub_f32_e64 v2, -v7, v2
	v_cvt_pk_bf16_f32 v2, v2, s0
	v_lshl_or_b32 v0, v2, 16, v0
	v_cndmask_b32_e64 v0, 0, v0, s[2:3]
	v_mov_b32_e32 v2, v1
	v_mul_f32_e32 v245, v245, v8
	v_pk_mul_f32 v[142:143], v[142:143], v[8:9] op_sel_hi:[1,0]
	v_mfma_f32_32x32x16_bf16 v[160:175], v[192:195], v[0:3], v[160:175]
	v_mul_f32_e64 v140, v140, v8
	v_mul_f32_e64 v141, v141, v8
	v_mul_f32_e64 v138, v138, v8
	v_mul_f32_e64 v139, v139, v8
	v_mul_f32_e64 v136, v136, v8
	v_mul_f32_e64 v137, v137, v8
	v_pk_mul_f32 v[134:135], v[134:135], v[8:9] op_sel_hi:[1,0]
	v_pk_mul_f32 v[132:133], v[132:133], v[8:9] op_sel_hi:[1,0]
	v_pk_mul_f32 v[130:131], v[130:131], v[8:9] op_sel_hi:[1,0]
	v_pk_mul_f32 v[128:129], v[128:129], v[8:9] op_sel_hi:[1,0]
	v_mfma_f32_32x32x16_bf16 v[144:159], v[192:195], v[0:3], v[144:159]
	v_mul_f32_e64 v126, v126, v8
	v_mul_f32_e64 v127, v127, v8
	v_mul_f32_e64 v124, v124, v8
	v_mul_f32_e64 v125, v125, v8
	v_mul_f32_e64 v122, v122, v8
	v_mul_f32_e64 v123, v123, v8
	v_pk_mul_f32 v[120:121], v[120:121], v[8:9] op_sel_hi:[1,0]
	v_pk_mul_f32 v[118:119], v[118:119], v[8:9] op_sel_hi:[1,0]
	v_pk_mul_f32 v[116:117], v[116:117], v[8:9] op_sel_hi:[1,0]
	v_pk_mul_f32 v[114:115], v[114:115], v[8:9] op_sel_hi:[1,0]
	v_pk_mul_f32 v[112:113], v[112:113], v[8:9] op_sel_hi:[1,0]
	s_branch .LBB0_2419
